# v18: v16 + hand-written CMP1 epilogue (silu via v_rcp, 4-wide interleave, paired bf16 lo/hi stores, 8 row-group bases)
# baseline (speedup 1.0000x reference)
.LBB0_561:
	s_and_b64 s[2:3], s[4:5], exec
	v_readlane_b32 s4, v255, 61
	v_mov_b32_e32 v64, v166
	v_readlane_b32 s12, v254, 5
	v_readlane_b32 s13, v254, 6
	v_readlane_b32 s14, v254, 7
	v_readlane_b32 s15, v254, 8
	v_readlane_b32 s16, v254, 9
	v_readlane_b32 s17, v254, 10
	s_waitcnt lgkmcnt(0)
	s_barrier
	v_readlane_b32 s18, v254, 11
	v_and_b32_e32 v65, 31, v64
	v_readlane_b32 s19, v254, 12
	s_mov_b64 s[12:13], s[16:17]
	v_readlane_b32 s5, v255, 62
	s_mov_b64 s[14:15], s[18:19]
	v_or3_b32 v66, v65, v174, s0
	s_cselect_b32 s5, s13, s15
	s_cselect_b32 s4, s12, s14
	v_lshlrev_b32_e32 v68, 2, v66
	global_load_dword v69, v68, s[4:5]
	v_readlane_b32 s36, v254, 13
	v_readlane_b32 s48, v254, 25
	v_readlane_b32 s49, v254, 26
	v_readlane_b32 s50, v254, 27
	v_readlane_b32 s51, v254, 28
	v_readlane_b32 s2, v255, 12
	s_cselect_b32 s1, s49, s51
	s_cselect_b32 s0, s48, s50
	s_and_b32 s2, s2, 30
	v_lshrrev_b32_e32 v64, 3, v64
	v_add_lshl_u32 v67, v172, s2, 6
	v_mov_b32_e32 v65, 0
	v_and_or_b32 v70, v64, 4, v67
	v_lshlrev_b32_e32 v64, 1, v66
	v_lshl_add_u64 v[66:67], s[0:1], 0, v[64:65]
	v_mul_u32_u24_e32 v64, 0x280, v70
	v_lshl_add_u64 v[64:65], v[66:67], 0, v[64:65]
	v_readlane_b32 s6, v255, 63
	v_readlane_b32 s7, v254, 0
	global_load_dword v68, v68, s[4:5] offset:128
	v_readlane_b32 s8, v254, 1
	v_readlane_b32 s9, v254, 2
	s_movk_i32 s2, 0x1000
	v_readlane_b32 s10, v254, 3
	v_readlane_b32 s11, v254, 4
	v_readlane_b32 s37, v254, 14
	v_readlane_b32 s38, v254, 15
	v_readlane_b32 s39, v254, 16
	v_readlane_b32 s40, v254, 17
	v_readlane_b32 s41, v254, 18
	v_readlane_b32 s42, v254, 19
	v_readlane_b32 s43, v254, 20
	v_readlane_b32 s44, v254, 21
	v_readlane_b32 s45, v254, 22
	v_readlane_b32 s46, v254, 23
	v_readlane_b32 s47, v254, 24
	s_waitcnt vmcnt(0)
	s_mov_b32 s3, 0
	s_mov_b32 s2, 0x1400
	v_lshl_add_u64 v[200:201], v[64:65], 0, s[2:3]
	s_mov_b32 s2, 0x2800
	v_lshl_add_u64 v[202:203], v[64:65], 0, s[2:3]
	s_mov_b32 s2, 0x3c00
	v_lshl_add_u64 v[204:205], v[64:65], 0, s[2:3]
	s_mov_b32 s2, 0x5000
	v_lshl_add_u64 v[206:207], v[64:65], 0, s[2:3]
	s_mov_b32 s2, 0x6400
	v_lshl_add_u64 v[208:209], v[64:65], 0, s[2:3]
	s_mov_b32 s2, 0x7800
	v_lshl_add_u64 v[210:211], v[64:65], 0, s[2:3]
	s_mov_b32 s2, 0x8c00
	v_lshl_add_u64 v[212:213], v[64:65], 0, s[2:3]
	v_add_f32_e32 v48, v48, v69
	v_add_f32_e32 v49, v49, v69
	v_add_f32_e32 v50, v50, v69
	v_add_f32_e32 v51, v51, v69
	v_mul_f32_e32 v80, 0xbfb8aa3b, v48
	v_mul_f32_e32 v81, 0xbfb8aa3b, v49
	v_mul_f32_e32 v82, 0xbfb8aa3b, v50
	v_mul_f32_e32 v83, 0xbfb8aa3b, v51
	v_exp_f32_e32 v80, v80
	v_exp_f32_e32 v81, v81
	v_exp_f32_e32 v82, v82
	v_exp_f32_e32 v83, v83
	v_add_f32_e32 v80, 1.0, v80
	v_add_f32_e32 v81, 1.0, v81
	v_add_f32_e32 v82, 1.0, v82
	v_add_f32_e32 v83, 1.0, v83
	v_rcp_f32_e32 v80, v80
	v_rcp_f32_e32 v81, v81
	v_rcp_f32_e32 v82, v82
	v_rcp_f32_e32 v83, v83
	v_mul_f32_e32 v48, v48, v80
	v_mul_f32_e32 v49, v49, v81
	v_mul_f32_e32 v50, v50, v82
	v_mul_f32_e32 v51, v51, v83
	v_cvt_pk_bf16_f32 v84, v48, v49
	v_cvt_pk_bf16_f32 v85, v50, v51
	global_store_short v[64:65], v84, off
	global_store_short_d16_hi v[64:65], v84, off offset:640
	global_store_short v[64:65], v85, off offset:1280
	global_store_short_d16_hi v[64:65], v85, off offset:1920
	v_add_f32_e32 v52, v52, v69
	v_add_f32_e32 v53, v53, v69
	v_add_f32_e32 v54, v54, v69
	v_add_f32_e32 v55, v55, v69
	v_mul_f32_e32 v80, 0xbfb8aa3b, v52
	v_mul_f32_e32 v81, 0xbfb8aa3b, v53
	v_mul_f32_e32 v82, 0xbfb8aa3b, v54
	v_mul_f32_e32 v83, 0xbfb8aa3b, v55
	v_exp_f32_e32 v80, v80
	v_exp_f32_e32 v81, v81
	v_exp_f32_e32 v82, v82
	v_exp_f32_e32 v83, v83
	v_add_f32_e32 v80, 1.0, v80
	v_add_f32_e32 v81, 1.0, v81
	v_add_f32_e32 v82, 1.0, v82
	v_add_f32_e32 v83, 1.0, v83
	v_rcp_f32_e32 v80, v80
	v_rcp_f32_e32 v81, v81
	v_rcp_f32_e32 v82, v82
	v_rcp_f32_e32 v83, v83
	v_mul_f32_e32 v52, v52, v80
	v_mul_f32_e32 v53, v53, v81
	v_mul_f32_e32 v54, v54, v82
	v_mul_f32_e32 v55, v55, v83
	v_cvt_pk_bf16_f32 v86, v52, v53
	v_cvt_pk_bf16_f32 v87, v54, v55
	global_store_short v[200:201], v86, off
	global_store_short_d16_hi v[200:201], v86, off offset:640
	global_store_short v[200:201], v87, off offset:1280
	global_store_short_d16_hi v[200:201], v87, off offset:1920
	v_add_f32_e32 v56, v56, v69
	v_add_f32_e32 v57, v57, v69
	v_add_f32_e32 v58, v58, v69
	v_add_f32_e32 v59, v59, v69
	v_mul_f32_e32 v80, 0xbfb8aa3b, v56
	v_mul_f32_e32 v81, 0xbfb8aa3b, v57
	v_mul_f32_e32 v82, 0xbfb8aa3b, v58
	v_mul_f32_e32 v83, 0xbfb8aa3b, v59
	v_exp_f32_e32 v80, v80
	v_exp_f32_e32 v81, v81
	v_exp_f32_e32 v82, v82
	v_exp_f32_e32 v83, v83
	v_add_f32_e32 v80, 1.0, v80
	v_add_f32_e32 v81, 1.0, v81
	v_add_f32_e32 v82, 1.0, v82
	v_add_f32_e32 v83, 1.0, v83
	v_rcp_f32_e32 v80, v80
	v_rcp_f32_e32 v81, v81
	v_rcp_f32_e32 v82, v82
	v_rcp_f32_e32 v83, v83
	v_mul_f32_e32 v56, v56, v80
	v_mul_f32_e32 v57, v57, v81
	v_mul_f32_e32 v58, v58, v82
	v_mul_f32_e32 v59, v59, v83
	v_cvt_pk_bf16_f32 v88, v56, v57
	v_cvt_pk_bf16_f32 v89, v58, v59
	global_store_short v[202:203], v88, off
	global_store_short_d16_hi v[202:203], v88, off offset:640
	global_store_short v[202:203], v89, off offset:1280
	global_store_short_d16_hi v[202:203], v89, off offset:1920
	v_add_f32_e32 v60, v60, v69
	v_add_f32_e32 v61, v61, v69
	v_add_f32_e32 v62, v62, v69
	v_add_f32_e32 v63, v63, v69
	v_mul_f32_e32 v80, 0xbfb8aa3b, v60
	v_mul_f32_e32 v81, 0xbfb8aa3b, v61
	v_mul_f32_e32 v82, 0xbfb8aa3b, v62
	v_mul_f32_e32 v83, 0xbfb8aa3b, v63
	v_exp_f32_e32 v80, v80
	v_exp_f32_e32 v81, v81
	v_exp_f32_e32 v82, v82
	v_exp_f32_e32 v83, v83
	v_add_f32_e32 v80, 1.0, v80
	v_add_f32_e32 v81, 1.0, v81
	v_add_f32_e32 v82, 1.0, v82
	v_add_f32_e32 v83, 1.0, v83
	v_rcp_f32_e32 v80, v80
	v_rcp_f32_e32 v81, v81
	v_rcp_f32_e32 v82, v82
	v_rcp_f32_e32 v83, v83
	v_mul_f32_e32 v60, v60, v80
	v_mul_f32_e32 v61, v61, v81
	v_mul_f32_e32 v62, v62, v82
	v_mul_f32_e32 v63, v63, v83
	v_cvt_pk_bf16_f32 v90, v60, v61
	v_cvt_pk_bf16_f32 v91, v62, v63
	global_store_short v[204:205], v90, off
	global_store_short_d16_hi v[204:205], v90, off offset:640
	global_store_short v[204:205], v91, off offset:1280
	global_store_short_d16_hi v[204:205], v91, off offset:1920
	v_add_f32_e32 v32, v32, v68
	v_add_f32_e32 v33, v33, v68
	v_add_f32_e32 v34, v34, v68
	v_add_f32_e32 v35, v35, v68
	v_mul_f32_e32 v80, 0xbfb8aa3b, v32
	v_mul_f32_e32 v81, 0xbfb8aa3b, v33
	v_mul_f32_e32 v82, 0xbfb8aa3b, v34
	v_mul_f32_e32 v83, 0xbfb8aa3b, v35
	v_exp_f32_e32 v80, v80
	v_exp_f32_e32 v81, v81
	v_exp_f32_e32 v82, v82
	v_exp_f32_e32 v83, v83
	v_add_f32_e32 v80, 1.0, v80
	v_add_f32_e32 v81, 1.0, v81
	v_add_f32_e32 v82, 1.0, v82
	v_add_f32_e32 v83, 1.0, v83
	v_rcp_f32_e32 v80, v80
	v_rcp_f32_e32 v81, v81
	v_rcp_f32_e32 v82, v82
	v_rcp_f32_e32 v83, v83
	v_mul_f32_e32 v32, v32, v80
	v_mul_f32_e32 v33, v33, v81
	v_mul_f32_e32 v34, v34, v82
	v_mul_f32_e32 v35, v35, v83
	v_cvt_pk_bf16_f32 v84, v32, v33
	v_cvt_pk_bf16_f32 v85, v34, v35
	global_store_short v[64:65], v84, off offset:64
	global_store_short_d16_hi v[64:65], v84, off offset:704
	global_store_short v[64:65], v85, off offset:1344
	global_store_short_d16_hi v[64:65], v85, off offset:1984
	v_add_f32_e32 v36, v36, v68
	v_add_f32_e32 v37, v37, v68
	v_add_f32_e32 v38, v38, v68
	v_add_f32_e32 v39, v39, v68
	v_mul_f32_e32 v80, 0xbfb8aa3b, v36
	v_mul_f32_e32 v81, 0xbfb8aa3b, v37
	v_mul_f32_e32 v82, 0xbfb8aa3b, v38
	v_mul_f32_e32 v83, 0xbfb8aa3b, v39
	v_exp_f32_e32 v80, v80
	v_exp_f32_e32 v81, v81
	v_exp_f32_e32 v82, v82
	v_exp_f32_e32 v83, v83
	v_add_f32_e32 v80, 1.0, v80
	v_add_f32_e32 v81, 1.0, v81
	v_add_f32_e32 v82, 1.0, v82
	v_add_f32_e32 v83, 1.0, v83
	v_rcp_f32_e32 v80, v80
	v_rcp_f32_e32 v81, v81
	v_rcp_f32_e32 v82, v82
	v_rcp_f32_e32 v83, v83
	v_mul_f32_e32 v36, v36, v80
	v_mul_f32_e32 v37, v37, v81
	v_mul_f32_e32 v38, v38, v82
	v_mul_f32_e32 v39, v39, v83
	v_cvt_pk_bf16_f32 v86, v36, v37
	v_cvt_pk_bf16_f32 v87, v38, v39
	global_store_short v[200:201], v86, off offset:64
	global_store_short_d16_hi v[200:201], v86, off offset:704
	global_store_short v[200:201], v87, off offset:1344
	global_store_short_d16_hi v[200:201], v87, off offset:1984
	v_add_f32_e32 v40, v40, v68
	v_add_f32_e32 v41, v41, v68
	v_add_f32_e32 v42, v42, v68
	v_add_f32_e32 v43, v43, v68
	v_mul_f32_e32 v80, 0xbfb8aa3b, v40
	v_mul_f32_e32 v81, 0xbfb8aa3b, v41
	v_mul_f32_e32 v82, 0xbfb8aa3b, v42
	v_mul_f32_e32 v83, 0xbfb8aa3b, v43
	v_exp_f32_e32 v80, v80
	v_exp_f32_e32 v81, v81
	v_exp_f32_e32 v82, v82
	v_exp_f32_e32 v83, v83
	v_add_f32_e32 v80, 1.0, v80
	v_add_f32_e32 v81, 1.0, v81
	v_add_f32_e32 v82, 1.0, v82
	v_add_f32_e32 v83, 1.0, v83
	v_rcp_f32_e32 v80, v80
	v_rcp_f32_e32 v81, v81
	v_rcp_f32_e32 v82, v82
	v_rcp_f32_e32 v83, v83
	v_mul_f32_e32 v40, v40, v80
	v_mul_f32_e32 v41, v41, v81
	v_mul_f32_e32 v42, v42, v82
	v_mul_f32_e32 v43, v43, v83
	v_cvt_pk_bf16_f32 v88, v40, v41
	v_cvt_pk_bf16_f32 v89, v42, v43
	global_store_short v[202:203], v88, off offset:64
	global_store_short_d16_hi v[202:203], v88, off offset:704
	global_store_short v[202:203], v89, off offset:1344
	global_store_short_d16_hi v[202:203], v89, off offset:1984
	v_add_f32_e32 v44, v44, v68
	v_add_f32_e32 v45, v45, v68
	v_add_f32_e32 v46, v46, v68
	v_add_f32_e32 v47, v47, v68
	v_mul_f32_e32 v80, 0xbfb8aa3b, v44
	v_mul_f32_e32 v81, 0xbfb8aa3b, v45
	v_mul_f32_e32 v82, 0xbfb8aa3b, v46
	v_mul_f32_e32 v83, 0xbfb8aa3b, v47
	v_exp_f32_e32 v80, v80
	v_exp_f32_e32 v81, v81
	v_exp_f32_e32 v82, v82
	v_exp_f32_e32 v83, v83
	v_add_f32_e32 v80, 1.0, v80
	v_add_f32_e32 v81, 1.0, v81
	v_add_f32_e32 v82, 1.0, v82
	v_add_f32_e32 v83, 1.0, v83
	v_rcp_f32_e32 v80, v80
	v_rcp_f32_e32 v81, v81
	v_rcp_f32_e32 v82, v82
	v_rcp_f32_e32 v83, v83
	v_mul_f32_e32 v44, v44, v80
	v_mul_f32_e32 v45, v45, v81
	v_mul_f32_e32 v46, v46, v82
	v_mul_f32_e32 v47, v47, v83
	v_cvt_pk_bf16_f32 v90, v44, v45
	v_cvt_pk_bf16_f32 v91, v46, v47
	global_store_short v[204:205], v90, off offset:64
	global_store_short_d16_hi v[204:205], v90, off offset:704
	global_store_short v[204:205], v91, off offset:1344
	global_store_short_d16_hi v[204:205], v91, off offset:1984
	v_add_f32_e32 v16, v16, v69
	v_add_f32_e32 v17, v17, v69
	v_add_f32_e32 v18, v18, v69
	v_add_f32_e32 v19, v19, v69
	v_mul_f32_e32 v80, 0xbfb8aa3b, v16
	v_mul_f32_e32 v81, 0xbfb8aa3b, v17
	v_mul_f32_e32 v82, 0xbfb8aa3b, v18
	v_mul_f32_e32 v83, 0xbfb8aa3b, v19
	v_exp_f32_e32 v80, v80
	v_exp_f32_e32 v81, v81
	v_exp_f32_e32 v82, v82
	v_exp_f32_e32 v83, v83
	v_add_f32_e32 v80, 1.0, v80
	v_add_f32_e32 v81, 1.0, v81
	v_add_f32_e32 v82, 1.0, v82
	v_add_f32_e32 v83, 1.0, v83
	v_rcp_f32_e32 v80, v80
	v_rcp_f32_e32 v81, v81
	v_rcp_f32_e32 v82, v82
	v_rcp_f32_e32 v83, v83
	v_mul_f32_e32 v16, v16, v80
	v_mul_f32_e32 v17, v17, v81
	v_mul_f32_e32 v18, v18, v82
	v_mul_f32_e32 v19, v19, v83
	v_cvt_pk_bf16_f32 v84, v16, v17
	v_cvt_pk_bf16_f32 v85, v18, v19
	global_store_short v[206:207], v84, off
	global_store_short_d16_hi v[206:207], v84, off offset:640
	global_store_short v[206:207], v85, off offset:1280
	global_store_short_d16_hi v[206:207], v85, off offset:1920
	v_add_f32_e32 v20, v20, v69
	v_add_f32_e32 v21, v21, v69
	v_add_f32_e32 v22, v22, v69
	v_add_f32_e32 v23, v23, v69
	v_mul_f32_e32 v80, 0xbfb8aa3b, v20
	v_mul_f32_e32 v81, 0xbfb8aa3b, v21
	v_mul_f32_e32 v82, 0xbfb8aa3b, v22
	v_mul_f32_e32 v83, 0xbfb8aa3b, v23
	v_exp_f32_e32 v80, v80
	v_exp_f32_e32 v81, v81
	v_exp_f32_e32 v82, v82
	v_exp_f32_e32 v83, v83
	v_add_f32_e32 v80, 1.0, v80
	v_add_f32_e32 v81, 1.0, v81
	v_add_f32_e32 v82, 1.0, v82
	v_add_f32_e32 v83, 1.0, v83
	v_rcp_f32_e32 v80, v80
	v_rcp_f32_e32 v81, v81
	v_rcp_f32_e32 v82, v82
	v_rcp_f32_e32 v83, v83
	v_mul_f32_e32 v20, v20, v80
	v_mul_f32_e32 v21, v21, v81
	v_mul_f32_e32 v22, v22, v82
	v_mul_f32_e32 v23, v23, v83
	v_cvt_pk_bf16_f32 v86, v20, v21
	v_cvt_pk_bf16_f32 v87, v22, v23
	global_store_short v[208:209], v86, off
	global_store_short_d16_hi v[208:209], v86, off offset:640
	global_store_short v[208:209], v87, off offset:1280
	global_store_short_d16_hi v[208:209], v87, off offset:1920
	v_add_f32_e32 v24, v24, v69
	v_add_f32_e32 v25, v25, v69
	v_add_f32_e32 v26, v26, v69
	v_add_f32_e32 v27, v27, v69
	v_mul_f32_e32 v80, 0xbfb8aa3b, v24
	v_mul_f32_e32 v81, 0xbfb8aa3b, v25
	v_mul_f32_e32 v82, 0xbfb8aa3b, v26
	v_mul_f32_e32 v83, 0xbfb8aa3b, v27
	v_exp_f32_e32 v80, v80
	v_exp_f32_e32 v81, v81
	v_exp_f32_e32 v82, v82
	v_exp_f32_e32 v83, v83
	v_add_f32_e32 v80, 1.0, v80
	v_add_f32_e32 v81, 1.0, v81
	v_add_f32_e32 v82, 1.0, v82
	v_add_f32_e32 v83, 1.0, v83
	v_rcp_f32_e32 v80, v80
	v_rcp_f32_e32 v81, v81
	v_rcp_f32_e32 v82, v82
	v_rcp_f32_e32 v83, v83
	v_mul_f32_e32 v24, v24, v80
	v_mul_f32_e32 v25, v25, v81
	v_mul_f32_e32 v26, v26, v82
	v_mul_f32_e32 v27, v27, v83
	v_cvt_pk_bf16_f32 v88, v24, v25
	v_cvt_pk_bf16_f32 v89, v26, v27
	global_store_short v[210:211], v88, off
	global_store_short_d16_hi v[210:211], v88, off offset:640
	global_store_short v[210:211], v89, off offset:1280
	global_store_short_d16_hi v[210:211], v89, off offset:1920
	v_add_f32_e32 v28, v28, v69
	v_add_f32_e32 v29, v29, v69
	v_add_f32_e32 v30, v30, v69
	v_add_f32_e32 v31, v31, v69
	v_mul_f32_e32 v80, 0xbfb8aa3b, v28
	v_mul_f32_e32 v81, 0xbfb8aa3b, v29
	v_mul_f32_e32 v82, 0xbfb8aa3b, v30
	v_mul_f32_e32 v83, 0xbfb8aa3b, v31
	v_exp_f32_e32 v80, v80
	v_exp_f32_e32 v81, v81
	v_exp_f32_e32 v82, v82
	v_exp_f32_e32 v83, v83
	v_add_f32_e32 v80, 1.0, v80
	v_add_f32_e32 v81, 1.0, v81
	v_add_f32_e32 v82, 1.0, v82
	v_add_f32_e32 v83, 1.0, v83
	v_rcp_f32_e32 v80, v80
	v_rcp_f32_e32 v81, v81
	v_rcp_f32_e32 v82, v82
	v_rcp_f32_e32 v83, v83
	v_mul_f32_e32 v28, v28, v80
	v_mul_f32_e32 v29, v29, v81
	v_mul_f32_e32 v30, v30, v82
	v_mul_f32_e32 v31, v31, v83
	v_cvt_pk_bf16_f32 v90, v28, v29
	v_cvt_pk_bf16_f32 v91, v30, v31
	global_store_short v[212:213], v90, off
	global_store_short_d16_hi v[212:213], v90, off offset:640
	global_store_short v[212:213], v91, off offset:1280
	global_store_short_d16_hi v[212:213], v91, off offset:1920
	v_add_f32_e32 v0, v0, v68
	v_add_f32_e32 v1, v1, v68
	v_add_f32_e32 v2, v2, v68
	v_add_f32_e32 v3, v3, v68
	v_mul_f32_e32 v80, 0xbfb8aa3b, v0
	v_mul_f32_e32 v81, 0xbfb8aa3b, v1
	v_mul_f32_e32 v82, 0xbfb8aa3b, v2
	v_mul_f32_e32 v83, 0xbfb8aa3b, v3
	v_exp_f32_e32 v80, v80
	v_exp_f32_e32 v81, v81
	v_exp_f32_e32 v82, v82
	v_exp_f32_e32 v83, v83
	v_add_f32_e32 v80, 1.0, v80
	v_add_f32_e32 v81, 1.0, v81
	v_add_f32_e32 v82, 1.0, v82
	v_add_f32_e32 v83, 1.0, v83
	v_rcp_f32_e32 v80, v80
	v_rcp_f32_e32 v81, v81
	v_rcp_f32_e32 v82, v82
	v_rcp_f32_e32 v83, v83
	v_mul_f32_e32 v0, v0, v80
	v_mul_f32_e32 v1, v1, v81
	v_mul_f32_e32 v2, v2, v82
	v_mul_f32_e32 v3, v3, v83
	v_cvt_pk_bf16_f32 v84, v0, v1
	v_cvt_pk_bf16_f32 v85, v2, v3
	global_store_short v[206:207], v84, off offset:64
	global_store_short_d16_hi v[206:207], v84, off offset:704
	global_store_short v[206:207], v85, off offset:1344
	global_store_short_d16_hi v[206:207], v85, off offset:1984
	v_add_f32_e32 v4, v4, v68
	v_add_f32_e32 v5, v5, v68
	v_add_f32_e32 v6, v6, v68
	v_add_f32_e32 v7, v7, v68
	v_mul_f32_e32 v80, 0xbfb8aa3b, v4
	v_mul_f32_e32 v81, 0xbfb8aa3b, v5
	v_mul_f32_e32 v82, 0xbfb8aa3b, v6
	v_mul_f32_e32 v83, 0xbfb8aa3b, v7
	v_exp_f32_e32 v80, v80
	v_exp_f32_e32 v81, v81
	v_exp_f32_e32 v82, v82
	v_exp_f32_e32 v83, v83
	v_add_f32_e32 v80, 1.0, v80
	v_add_f32_e32 v81, 1.0, v81
	v_add_f32_e32 v82, 1.0, v82
	v_add_f32_e32 v83, 1.0, v83
	v_rcp_f32_e32 v80, v80
	v_rcp_f32_e32 v81, v81
	v_rcp_f32_e32 v82, v82
	v_rcp_f32_e32 v83, v83
	v_mul_f32_e32 v4, v4, v80
	v_mul_f32_e32 v5, v5, v81
	v_mul_f32_e32 v6, v6, v82
	v_mul_f32_e32 v7, v7, v83
	v_cvt_pk_bf16_f32 v86, v4, v5
	v_cvt_pk_bf16_f32 v87, v6, v7
	global_store_short v[208:209], v86, off offset:64
	global_store_short_d16_hi v[208:209], v86, off offset:704
	global_store_short v[208:209], v87, off offset:1344
	global_store_short_d16_hi v[208:209], v87, off offset:1984
	v_add_f32_e32 v8, v8, v68
	v_add_f32_e32 v9, v9, v68
	v_add_f32_e32 v10, v10, v68
	v_add_f32_e32 v11, v11, v68
	v_mul_f32_e32 v80, 0xbfb8aa3b, v8
	v_mul_f32_e32 v81, 0xbfb8aa3b, v9
	v_mul_f32_e32 v82, 0xbfb8aa3b, v10
	v_mul_f32_e32 v83, 0xbfb8aa3b, v11
	v_exp_f32_e32 v80, v80
	v_exp_f32_e32 v81, v81
	v_exp_f32_e32 v82, v82
	v_exp_f32_e32 v83, v83
	v_add_f32_e32 v80, 1.0, v80
	v_add_f32_e32 v81, 1.0, v81
	v_add_f32_e32 v82, 1.0, v82
	v_add_f32_e32 v83, 1.0, v83
	v_rcp_f32_e32 v80, v80
	v_rcp_f32_e32 v81, v81
	v_rcp_f32_e32 v82, v82
	v_rcp_f32_e32 v83, v83
	v_mul_f32_e32 v8, v8, v80
	v_mul_f32_e32 v9, v9, v81
	v_mul_f32_e32 v10, v10, v82
	v_mul_f32_e32 v11, v11, v83
	v_cvt_pk_bf16_f32 v88, v8, v9
	v_cvt_pk_bf16_f32 v89, v10, v11
	global_store_short v[210:211], v88, off offset:64
	global_store_short_d16_hi v[210:211], v88, off offset:704
	global_store_short v[210:211], v89, off offset:1344
	global_store_short_d16_hi v[210:211], v89, off offset:1984
	v_add_f32_e32 v12, v12, v68
	v_add_f32_e32 v13, v13, v68
	v_add_f32_e32 v14, v14, v68
	v_add_f32_e32 v15, v15, v68
	v_mul_f32_e32 v80, 0xbfb8aa3b, v12
	v_mul_f32_e32 v81, 0xbfb8aa3b, v13
	v_mul_f32_e32 v82, 0xbfb8aa3b, v14
	v_mul_f32_e32 v83, 0xbfb8aa3b, v15
	v_exp_f32_e32 v80, v80
	v_exp_f32_e32 v81, v81
	v_exp_f32_e32 v82, v82
	v_exp_f32_e32 v83, v83
	v_add_f32_e32 v80, 1.0, v80
	v_add_f32_e32 v81, 1.0, v81
	v_add_f32_e32 v82, 1.0, v82
	v_add_f32_e32 v83, 1.0, v83
	v_rcp_f32_e32 v80, v80
	v_rcp_f32_e32 v81, v81
	v_rcp_f32_e32 v82, v82
	v_rcp_f32_e32 v83, v83
	v_mul_f32_e32 v12, v12, v80
	v_mul_f32_e32 v13, v13, v81
	v_mul_f32_e32 v14, v14, v82
	v_mul_f32_e32 v15, v15, v83
	v_cvt_pk_bf16_f32 v90, v12, v13
	v_cvt_pk_bf16_f32 v91, v14, v15
	global_store_short v[212:213], v90, off offset:64
	global_store_short_d16_hi v[212:213], v90, off offset:704
	global_store_short v[212:213], v91, off offset:1344
	global_store_short_d16_hi v[212:213], v91, off offset:1984
	s_waitcnt lgkmcnt(0)
	s_barrier
	s_waitcnt vmcnt(0)
	s_barrier
	s_mov_b64 s[4:5], exec
	v_readlane_b32 s0, v254, 29
	v_readlane_b32 s1, v254, 30
	s_and_b64 s[0:1], s[4:5], s[0:1]
	s_mov_b64 exec, s[0:1]
	s_cbranch_execz .Lc2_pub_done
	buffer_wbl2 sc1
	s_waitcnt vmcnt(0)
	v_mov_b32_e32 v0, 0
	v_mov_b32_e32 v1, 1
	global_atomic_add v0, v1, s[68:69] offset:160
